# v13 + static s_setprio 1 for waves 4-7 inside the attention super-tile loop (strategy 4: static priority for the younger half)
# speedup vs baseline: 1.0228x; 1.0228x over previous
; DI void attn_phase(const Params& p, unsigned char* smem) {
;     ...
;         const int nst = (ntiles + 1) >> 1;
;         unsigned zz = 0; asm volatile("" : "+v"(zz));
;         uint4 rk0, rk1 = make_uint4(zz, zz, zz, zz), rk2 = rk1, rv0 = rk1, rv1 = rk1;
;         { const bool h2 = 1 < ntiles;
;           rk0 = *(const uint4*)(kbase + ko0);
;           if (kr1 < 64 || h2) rk1 = *(const uint4*)(kbase + ko1);
;           if (h2) rk2 = *(const uint4*)(kbase + ko2);
;           if (vch < 8 || h2) { rv0 = *(const uint4*)(vbase + vo0); rv1 = *(const uint4*)(vbase + vo1); } }
;         *(uint4*)(sbuf + kd0) = rk0; *(uint4*)(sbuf + kd1) = rk1; *(uint4*)(sbuf + kd2) = rk2;
;         *(uint4*)(sbuf + vd0) = rv0; *(uint4*)(sbuf + vd1) = rv1;
;         __syncthreads();
;         for (int st_ = 0; st_ < nst; ++st_) {
.LBB0_935:
	s_or_b64 exec, exec, s[0:1]
	s_add_i32 s0, s19, 1
	s_lshr_b32 s30, s0, 1
	s_add_i32 s0, s23, s18
	s_and_b32 s0, s0, 7
	s_add_i32 s31, s19, -3
	s_mulk_i32 s0, 0xc0
	s_add_u32 s0, s14, s0
	s_addc_u32 s1, s7, 0
	s_add_u32 s0, s62, s0
	v_ashrrev_i32_e32 v193, 31, v192
	s_addc_u32 s1, s63, s1
	s_sub_i32 s42, 1, s30
	s_movk_i32 s50, 0x100
	s_mov_b32 s43, 2
	s_mov_b32 s44, 2
	s_waitcnt vmcnt(4)
	ds_write_b128 v165, v[32:35] offset:46080
	s_waitcnt vmcnt(3)
	ds_write_b128 v175, v[24:27] offset:46080
	s_waitcnt vmcnt(2)
	ds_write_b128 v156, v[28:31] offset:46080
	s_waitcnt vmcnt(1)
	ds_write_b128 v227, v[36:39]
	s_waitcnt vmcnt(0)
	ds_write_b128 v228, v[40:43]
	s_waitcnt lgkmcnt(0)
	s_barrier
	v_readfirstlane_b32 s6, v250
	s_nop 3
	s_cmpk_ge_u32 s6, 0x100
	s_cbranch_scc0 .Lattn_noprio
	s_setprio 1
.Lattn_noprio:
	s_branch .LBB0_937

; DI unsigned pack2(float lo, float hi) { const f32n2 v = {lo, hi}; return __builtin_bit_cast(unsigned, __builtin_convertvector(v, bf16n2)); }
; DI void attn_phase(const Params& p, unsigned char* smem) {
;     ...
;         if (wtiles > 0) {
; #pragma unroll
;             for (int qs = 0; qs < 2; ++qs) {
;                 float l = lrow[qs]; l += __shfl_xor(l, 16); l += __shfl_xor(l, 32);
;                 const float inv = 1.f / l;
;                 const int row = qrow0 + 32 * wave + 16 * qs + fr;
; #pragma unroll
;                 for (int dt = 0; dt < 4; ++dt) {
;                     uint2 o; o.x = pack2(ot[dt][qs][0] * inv, ot[dt][qs][1] * inv); o.y = pack2(ot[dt][qs][2] * inv, ot[dt][qs][3] * inv);
;                     *(uint2*)(CAT + (size_t)row * 1024 + h * 64 + 16 * dt + 4 * g) = o;
;                 }
;             }
;         }
.LBB0_959:
	s_setprio 0
	s_and_saveexec_b64 s[0:1], s[40:41]
	s_cbranch_execz .LBB0_903
	v_and_b32_e32 v1, 64, v251
	v_xor_b32_e32 v0, 16, v251
	v_add_u32_e32 v1, 64, v1
	v_cmp_lt_i32_e32 vcc, v0, v1
	v_xor_b32_e32 v2, 32, v251
	s_lshl_b32 s50, s27, 1
	v_cndmask_b32_e32 v0, v251, v0, vcc
	v_lshlrev_b32_e32 v3, 2, v0
	ds_bpermute_b32 v0, v3, v200
	v_cmp_lt_i32_e32 vcc, v2, v1
	s_waitcnt lgkmcnt(0)
	v_add_f32_e32 v0, v200, v0
	v_cndmask_b32_e32 v1, v251, v2, vcc
	v_lshlrev_b32_e32 v10, 2, v1
	v_mov_b32_e32 v1, v0
	s_waitcnt lgkmcnt(0)
	s_nop 1
	v_permlane32_swap_b32_e32 v0, v1
	v_add_f32_e32 v2, v0, v1
	v_lshl_add_u64 v[0:1], v[176:177], 0, s[50:51]
	v_rcp_f32_e32 v4, v2
	s_nop 0
	v_mul_f32_e32 v2, 1.0, v4
	v_lshlrev_b64 v[4:5], 11, v[190:191]
	v_pk_mul_f32 v[6:7], v[60:61], v[2:3] op_sel_hi:[1,0]
	v_pk_mul_f32 v[8:9], v[62:63], v[2:3] op_sel_hi:[1,0]
	v_lshl_add_u64 v[4:5], v[0:1], 0, v[4:5]
	v_cvt_pk_bf16_f32 v6, v6, v7
	v_cvt_pk_bf16_f32 v7, v8, v9
	global_store_dwordx2 v[4:5], v[6:7], off
	v_pk_mul_f32 v[6:7], v[48:49], v[2:3] op_sel_hi:[1,0]
	v_pk_mul_f32 v[8:9], v[50:51], v[2:3] op_sel_hi:[1,0]
	ds_bpermute_b32 v3, v3, v201
	v_cvt_pk_bf16_f32 v6, v6, v7
	v_cvt_pk_bf16_f32 v7, v8, v9
	global_store_dwordx2 v[4:5], v[6:7], off offset:32
	s_waitcnt lgkmcnt(0)
	v_pk_mul_f32 v[6:7], v[72:73], v[2:3] op_sel_hi:[1,0]
	v_pk_mul_f32 v[8:9], v[74:75], v[2:3] op_sel_hi:[1,0]
	v_add_f32_e32 v3, v201, v3
	ds_bpermute_b32 v10, v10, v3
	v_cvt_pk_bf16_f32 v6, v6, v7
	v_cvt_pk_bf16_f32 v7, v8, v9
	global_store_dwordx2 v[4:5], v[6:7], off offset:64
	v_pk_mul_f32 v[6:7], v[68:69], v[2:3] op_sel_hi:[1,0]
	s_waitcnt lgkmcnt(0)
	v_add_f32_e32 v8, v3, v10
	v_div_scale_f32 v9, s[6:7], v8, v8, 1.0
	v_rcp_f32_e32 v10, v9
	v_pk_mul_f32 v[2:3], v[70:71], v[2:3] op_sel_hi:[1,0]
	v_cvt_pk_bf16_f32 v6, v6, v7
	v_cvt_pk_bf16_f32 v7, v2, v3
	v_fma_f32 v2, -v9, v10, 1.0
	v_fmac_f32_e32 v10, v2, v10
	v_div_scale_f32 v2, vcc, 1.0, v8, 1.0
	v_mul_f32_e32 v3, v2, v10
	global_store_dwordx2 v[4:5], v[6:7], off offset:96
	v_fma_f32 v4, -v9, v3, v2
	v_fmac_f32_e32 v3, v4, v10
	v_fma_f32 v2, -v9, v3, v2
	v_div_fmas_f32 v2, v2, v10, v3
	v_div_fixup_f32 v2, v2, v8, 1.0
	v_lshlrev_b64 v[4:5], 11, v[192:193]
	v_lshl_add_u64 v[0:1], v[0:1], 0, v[4:5]
	v_pk_mul_f32 v[4:5], v[64:65], v[2:3] op_sel_hi:[1,0]
	v_pk_mul_f32 v[6:7], v[66:67], v[2:3] op_sel_hi:[1,0]
	v_cvt_pk_bf16_f32 v4, v4, v5
	v_cvt_pk_bf16_f32 v5, v6, v7
	global_store_dwordx2 v[0:1], v[4:5], off
	v_pk_mul_f32 v[4:5], v[56:57], v[2:3] op_sel_hi:[1,0]
	v_pk_mul_f32 v[6:7], v[58:59], v[2:3] op_sel_hi:[1,0]
	v_cvt_pk_bf16_f32 v4, v4, v5
	v_cvt_pk_bf16_f32 v5, v6, v7
	global_store_dwordx2 v[0:1], v[4:5], off offset:32
	v_pk_mul_f32 v[4:5], v[52:53], v[2:3] op_sel_hi:[1,0]
	v_pk_mul_f32 v[6:7], v[54:55], v[2:3] op_sel_hi:[1,0]
	v_cvt_pk_bf16_f32 v4, v4, v5
	v_cvt_pk_bf16_f32 v5, v6, v7
	global_store_dwordx2 v[0:1], v[4:5], off offset:64
	v_pk_mul_f32 v[4:5], v[44:45], v[2:3] op_sel_hi:[1,0]
	v_pk_mul_f32 v[2:3], v[46:47], v[2:3] op_sel_hi:[1,0]
	v_cvt_pk_bf16_f32 v4, v4, v5
	v_cvt_pk_bf16_f32 v5, v2, v3
	global_store_dwordx2 v[0:1], v[4:5], off offset:96
	s_branch .LBB0_903
